# barrier / panel-sync poll loops: s_sleep 1 removed from each poll iteration (strategy 9 loop-edge edit)
# speedup vs baseline: 1.0004x; 1.0004x over previous
; __global__ void __launch_bounds__(512, 2) mk_fwd(Args a) {
;     ...
;     if (hi < 0) cg::this_grid().sync();
.LBB0_16:
	s_nop 0
	global_load_dword v2, v0, s[4:5] offset:32 sc1
	s_waitcnt vmcnt(0)
	v_and_b32_e32 v2, 0xffff0000, v2
	v_cmp_ne_u32_e32 vcc, v2, v1
	s_or_b64 s[6:7], vcc, s[6:7]
	s_andn2_b64 exec, exec, s[6:7]
	s_cbranch_execnz .LBB0_16

; __device__ __forceinline__ unsigned xb_ld(unsigned* p)              { return __hip_atomic_load(p, __ATOMIC_RELAXED, __HIP_MEMORY_SCOPE_AGENT); }
; __device__ __forceinline__ void xcd_barrier_complete(unsigned* bar, unsigned x, unsigned& nloc, unsigned& nx) {
;     const unsigned G = gridDim.x * gridDim.y * gridDim.z;
;     unsigned sum, cnt, mine, sp = 0u;
;     for (;;) {
;         sum = 0u; cnt = 0u; mine = 0u;
; #pragma unroll
;         for (unsigned j = 0; j < 16; ++j) { const unsigned c = xb_ld(&bar[XB_XCNT(j)]); sum += c; cnt += (c > 0u) ? 1u : 0u; mine = (j == x) ? c : mine; }
;         if (sum == G) break;
;         __builtin_amdgcn_s_sleep(1);
;         if ((++sp & 255u) == 0u) { if (xb_ld(&bar[XB_TMO])) break; if (sp > XB_SPIN_CAP) { atomicAdd(&bar[XB_TMO], 1u); break; } }
;     }
;     nloc = mine > 0u ? mine : 1u; nx = cnt > 0u ? cnt : 1u;
; }
.LBB0_77:
	global_load_dword v15, v16, s[42:43] offset:1024 sc1
	global_load_dword v0, v16, s[42:43] offset:1280 sc1
	global_load_dword v1, v16, s[42:43] offset:1536 sc1
	global_load_dword v2, v16, s[42:43] offset:1792 sc1
	global_load_dword v3, v16, s[42:43] offset:2048 sc1
	global_load_dword v4, v16, s[42:43] offset:2304 sc1
	global_load_dword v5, v16, s[42:43] offset:2560 sc1
	global_load_dword v6, v16, s[42:43] offset:2816 sc1
	global_load_dword v7, v16, s[42:43] offset:3072 sc1
	global_load_dword v8, v16, s[42:43] offset:3328 sc1
	global_load_dword v9, v16, s[42:43] offset:3584 sc1
	global_load_dword v10, v16, s[42:43] offset:3840 sc1
	global_load_dword v11, v16, s[4:5] sc1
	global_load_dword v12, v16, s[6:7] sc1
	global_load_dword v13, v16, s[8:9] sc1
	global_load_dword v14, v16, s[10:11] sc1
	s_mov_b64 s[12:13], -1
	s_mov_b64 s[14:15], -1
	s_waitcnt vmcnt(14)
	v_add_u32_e32 v17, v0, v15
	s_waitcnt vmcnt(13)
	v_add_u32_e32 v17, v17, v1
	s_waitcnt vmcnt(12)
	v_add_u32_e32 v17, v17, v2
	s_waitcnt vmcnt(11)
	v_add_u32_e32 v17, v17, v3
	s_waitcnt vmcnt(10)
	v_add_u32_e32 v17, v17, v4
	s_waitcnt vmcnt(9)
	v_add_u32_e32 v17, v17, v5
	s_waitcnt vmcnt(8)
	v_add_u32_e32 v17, v17, v6
	s_waitcnt vmcnt(7)
	v_add_u32_e32 v17, v17, v7
	s_waitcnt vmcnt(6)
	v_add_u32_e32 v17, v17, v8
	s_waitcnt vmcnt(5)
	v_add_u32_e32 v17, v17, v9
	s_waitcnt vmcnt(4)
	v_add_u32_e32 v17, v17, v10
	s_waitcnt vmcnt(3)
	v_add_u32_e32 v17, v17, v11
	s_waitcnt vmcnt(2)
	v_add_u32_e32 v17, v17, v12
	s_waitcnt vmcnt(1)
	v_add_u32_e32 v17, v17, v13
	s_waitcnt vmcnt(0)
	v_add_u32_e32 v17, v17, v14
	v_cmp_eq_u32_e32 vcc, s18, v17
	s_cbranch_vccnz .LBB0_76
	s_and_b32 s12, s19, 0xff
	s_cmp_eq_u32 s12, 0
	s_mov_b64 s[12:13], -1
	s_mov_b64 s[16:17], -1
	s_nop 0
	s_cbranch_scc0 .LBB0_81
	global_load_dword v17, v16, s[42:43] offset:512 sc1
	s_waitcnt vmcnt(0)
	v_cmp_eq_u32_e32 vcc, 0, v17
	s_cbranch_vccnz .LBB0_83
	s_mov_b64 s[16:17], 0

; __device__ __forceinline__ unsigned xb_ld(unsigned* p)              { return __hip_atomic_load(p, __ATOMIC_RELAXED, __HIP_MEMORY_SCOPE_AGENT); }
; __device__ __forceinline__ unsigned xb_add(unsigned* p, unsigned v) { return __hip_atomic_fetch_add(p, v, __ATOMIC_RELAXED, __HIP_MEMORY_SCOPE_AGENT); }
; #define XB_SPIN(cond, bar) do { unsigned _sp = 0; while (cond) { __builtin_amdgcn_s_sleep(1); \
;     if ((++_sp & 255u) == 0u) { if (xb_ld(&(bar)[XB_TMO])) break; if (_sp > XB_SPIN_CAP) { atomicAdd(&(bar)[XB_TMO], 1u); break; } } } } while (0)
; template <bool FLUSH> __device__ __forceinline__ void xcd_barrier(const XcdBarrier& b) {
;     ...
;             const unsigned og = xb_add(&bar[XB_TOP], 1u);
;             const unsigned tg = og / nx;
;             if (og + 1u == (tg + 1u) * nx) xb_add(&bar[XB_TOPGEN], 1u);
;             else XB_SPIN(xb_ld(&bar[XB_TOPGEN]) == tg, bar);
;             __builtin_amdgcn_fence(__ATOMIC_ACQUIRE, "agent");
;             xb_add(&bar[XB_XGEN(b.x)], 1u);
;             asm volatile("s_waitcnt vmcnt(0)" ::: "memory");
;         } else {
;             XB_SPIN(xb_ld(&bar[XB_XGEN(b.x)]) == gen, bar);
;             __builtin_amdgcn_fence(__ATOMIC_ACQUIRE, "agent");
;             asm volatile("s_waitcnt vmcnt(0)" ::: "memory");
;         }
.LBB0_91:
	s_and_b32 s18, s22, 0xff
	s_mov_b64 s[16:17], -1
	s_cmp_lg_u32 s18, 0
	s_mov_b64 s[20:21], -1
	s_nop 0
	s_cbranch_scc1 .LBB0_94
	global_load_dword v2, v0, s[42:43] offset:512 sc1
	s_waitcnt vmcnt(0)
	v_cmp_eq_u32_e32 vcc, 0, v2
	s_cbranch_vccnz .LBB0_96
	s_mov_b64 s[20:21], 0
	s_mov_b64 s[18:19], -1

; __device__ __forceinline__ unsigned xb_ld(unsigned* p)              { return __hip_atomic_load(p, __ATOMIC_RELAXED, __HIP_MEMORY_SCOPE_AGENT); }
; __device__ __forceinline__ unsigned xb_add(unsigned* p, unsigned v) { return __hip_atomic_fetch_add(p, v, __ATOMIC_RELAXED, __HIP_MEMORY_SCOPE_AGENT); }
; #define XB_SPIN(cond, bar) do { unsigned _sp = 0; while (cond) { __builtin_amdgcn_s_sleep(1); \
;     if ((++_sp & 255u) == 0u) { if (xb_ld(&(bar)[XB_TMO])) break; if (_sp > XB_SPIN_CAP) { atomicAdd(&(bar)[XB_TMO], 1u); break; } } } } while (0)
; template <bool FLUSH> __device__ __forceinline__ void xcd_barrier(const XcdBarrier& b) {
;     ...
;             const unsigned og = xb_add(&bar[XB_TOP], 1u);
;             const unsigned tg = og / nx;
;             if (og + 1u == (tg + 1u) * nx) xb_add(&bar[XB_TOPGEN], 1u);
;             else XB_SPIN(xb_ld(&bar[XB_TOPGEN]) == tg, bar);
;             __builtin_amdgcn_fence(__ATOMIC_ACQUIRE, "agent");
;             xb_add(&bar[XB_XGEN(b.x)], 1u);
;             asm volatile("s_waitcnt vmcnt(0)" ::: "memory");
;         } else {
;             XB_SPIN(xb_ld(&bar[XB_XGEN(b.x)]) == gen, bar);
;             __builtin_amdgcn_fence(__ATOMIC_ACQUIRE, "agent");
;             asm volatile("s_waitcnt vmcnt(0)" ::: "memory");
;         }
.LBB0_105:
	s_and_b32 s18, s24, 0xff
	s_cmp_lg_u32 s18, 0
	s_mov_b64 s[20:21], -1
	s_nop 0
	s_cbranch_scc1 .LBB0_108
	global_load_dword v1, v0, s[10:11] sc1
	s_waitcnt vmcnt(0)
	v_cmp_eq_u32_e32 vcc, 0, v1
	s_cbranch_vccnz .LBB0_110
	s_mov_b64 s[20:21], 0
	s_mov_b64 s[18:19], -1

; __device__ __forceinline__ void panel_sync(unsigned* w) {
;     asm volatile("s_waitcnt vmcnt(0)" ::: "memory"); __syncthreads();
;     if (threadIdx.x == 0) { __hip_atomic_fetch_add(w, 1u, __ATOMIC_RELAXED, __HIP_MEMORY_SCOPE_AGENT); unsigned sp = 0;
;         while (__hip_atomic_load(w, __ATOMIC_RELAXED, __HIP_MEMORY_SCOPE_AGENT) < 4u) { __builtin_amdgcn_s_sleep(1); if (++sp > (1u << 22)) break; }
;         __builtin_amdgcn_fence(__ATOMIC_ACQUIRE, "agent"); asm volatile("s_waitcnt vmcnt(0)" ::: "memory"); }
;     __syncthreads();
; }
.LBB0_642:
	global_load_dword v1, v0, s[4:5] sc1
	s_mov_b64 s[6:7], -1
	s_waitcnt vmcnt(0)
	v_cmp_lt_u32_e32 vcc, 3, v1
	s_cbranch_vccnz .LBB0_641
	s_nop 0
	global_load_dword v1, v0, s[4:5] sc1
	s_waitcnt vmcnt(0)
	v_cmp_gt_u32_e32 vcc, 4, v1
	s_cbranch_vccz .LBB0_641
	s_nop 0
	global_load_dword v1, v0, s[4:5] sc1
	s_waitcnt vmcnt(0)
	v_cmp_gt_u32_e32 vcc, 4, v1
	s_cbranch_vccz .LBB0_641
	s_nop 0
	global_load_dword v1, v0, s[4:5] sc1
	s_waitcnt vmcnt(0)
	v_cmp_gt_u32_e32 vcc, 4, v1
	s_cbranch_vccz .LBB0_641
	s_nop 0
	global_load_dword v1, v0, s[4:5] sc1
	s_waitcnt vmcnt(0)
	v_cmp_gt_u32_e32 vcc, 4, v1
	s_cbranch_vccz .LBB0_641
	s_add_i32 s12, s12, -5
	s_cmp_eq_u32 s12, 0
	s_cselect_b64 s[6:7], -1, 0
	s_nop 0
	s_branch .LBB0_641

; __device__ __forceinline__ void panel_sync(unsigned* w) {
;     asm volatile("s_waitcnt vmcnt(0)" ::: "memory"); __syncthreads();
;     if (threadIdx.x == 0) { __hip_atomic_fetch_add(w, 1u, __ATOMIC_RELAXED, __HIP_MEMORY_SCOPE_AGENT); unsigned sp = 0;
;         while (__hip_atomic_load(w, __ATOMIC_RELAXED, __HIP_MEMORY_SCOPE_AGENT) < 4u) { __builtin_amdgcn_s_sleep(1); if (++sp > (1u << 22)) break; }
;         __builtin_amdgcn_fence(__ATOMIC_ACQUIRE, "agent"); asm volatile("s_waitcnt vmcnt(0)" ::: "memory"); }
;     __syncthreads();
; }
.LBB0_858:
	global_load_dword v1, v0, s[6:7] sc1
	s_mov_b64 s[16:17], -1
	s_waitcnt vmcnt(0)
	v_cmp_lt_u32_e32 vcc, 3, v1
	s_cbranch_vccnz .LBB0_857
	s_nop 0
	global_load_dword v1, v0, s[6:7] sc1
	s_waitcnt vmcnt(0)
	v_cmp_gt_u32_e32 vcc, 4, v1
	s_cbranch_vccz .LBB0_857
	s_nop 0
	global_load_dword v1, v0, s[6:7] sc1
	s_waitcnt vmcnt(0)
	v_cmp_gt_u32_e32 vcc, 4, v1
	s_cbranch_vccz .LBB0_857
	s_nop 0
	global_load_dword v1, v0, s[6:7] sc1
	s_waitcnt vmcnt(0)
	v_cmp_gt_u32_e32 vcc, 4, v1
	s_cbranch_vccz .LBB0_857
	s_nop 0
	global_load_dword v1, v0, s[6:7] sc1
	s_waitcnt vmcnt(0)
	v_cmp_gt_u32_e32 vcc, 4, v1
	s_cbranch_vccz .LBB0_857
	s_add_i32 s18, s18, -5
	s_cmp_eq_u32 s18, 0
	s_cselect_b64 s[16:17], -1, 0
	s_nop 0
	s_branch .LBB0_857

; __device__ __forceinline__ void panel_sync(unsigned* w) {
;     asm volatile("s_waitcnt vmcnt(0)" ::: "memory"); __syncthreads();
;     if (threadIdx.x == 0) { __hip_atomic_fetch_add(w, 1u, __ATOMIC_RELAXED, __HIP_MEMORY_SCOPE_AGENT); unsigned sp = 0;
;         while (__hip_atomic_load(w, __ATOMIC_RELAXED, __HIP_MEMORY_SCOPE_AGENT) < 4u) { __builtin_amdgcn_s_sleep(1); if (++sp > (1u << 22)) break; }
;         __builtin_amdgcn_fence(__ATOMIC_ACQUIRE, "agent"); asm volatile("s_waitcnt vmcnt(0)" ::: "memory"); }
;     __syncthreads();
; }
.LBB0_1677:
	global_load_dword v1, v0, s[6:7] sc1
	s_mov_b64 s[10:11], -1
	s_waitcnt vmcnt(0)
	v_cmp_lt_u32_e32 vcc, 3, v1
	s_cbranch_vccnz .LBB0_1676
	s_nop 0
	global_load_dword v1, v0, s[6:7] sc1
	s_waitcnt vmcnt(0)
	v_cmp_gt_u32_e32 vcc, 4, v1
	s_cbranch_vccz .LBB0_1676
	s_nop 0
	global_load_dword v1, v0, s[6:7] sc1
	s_waitcnt vmcnt(0)
	v_cmp_gt_u32_e32 vcc, 4, v1
	s_cbranch_vccz .LBB0_1676
	s_nop 0
	global_load_dword v1, v0, s[6:7] sc1
	s_waitcnt vmcnt(0)
	v_cmp_gt_u32_e32 vcc, 4, v1
	s_cbranch_vccz .LBB0_1676
	s_nop 0
	global_load_dword v1, v0, s[6:7] sc1
	s_waitcnt vmcnt(0)
	v_cmp_gt_u32_e32 vcc, 4, v1
	s_cbranch_vccz .LBB0_1676
	s_add_i32 s12, s12, -5
	s_cmp_eq_u32 s12, 0
	s_cselect_b64 s[10:11], -1, 0
	s_nop 0
	s_branch .LBB0_1676

; __device__ __forceinline__ unsigned xb_ld(unsigned* p)              { return __hip_atomic_load(p, __ATOMIC_RELAXED, __HIP_MEMORY_SCOPE_AGENT); }
; __device__ __forceinline__ void xcd_barrier_complete(unsigned* bar, unsigned x, unsigned& nloc, unsigned& nx) {
;     const unsigned G = gridDim.x * gridDim.y * gridDim.z;
;     unsigned sum, cnt, mine, sp = 0u;
;     for (;;) {
;         sum = 0u; cnt = 0u; mine = 0u;
; #pragma unroll
;         for (unsigned j = 0; j < 16; ++j) { const unsigned c = xb_ld(&bar[XB_XCNT(j)]); sum += c; cnt += (c > 0u) ? 1u : 0u; mine = (j == x) ? c : mine; }
;         if (sum == G) break;
;         __builtin_amdgcn_s_sleep(1);
;         if ((++sp & 255u) == 0u) { if (xb_ld(&bar[XB_TMO])) break; if (sp > XB_SPIN_CAP) { atomicAdd(&bar[XB_TMO], 1u); break; } }
;     }
;     nloc = mine > 0u ? mine : 1u; nx = cnt > 0u ? cnt : 1u;
; }
.LBB0_2189:
	global_load_dword v15, v16, s[42:43] offset:1024 sc1
	global_load_dword v0, v16, s[42:43] offset:1280 sc1
	global_load_dword v1, v16, s[42:43] offset:1536 sc1
	global_load_dword v2, v16, s[42:43] offset:1792 sc1
	global_load_dword v3, v16, s[42:43] offset:2048 sc1
	global_load_dword v4, v16, s[42:43] offset:2304 sc1
	global_load_dword v5, v16, s[42:43] offset:2560 sc1
	global_load_dword v6, v16, s[42:43] offset:2816 sc1
	global_load_dword v7, v16, s[42:43] offset:3072 sc1
	global_load_dword v8, v16, s[42:43] offset:3328 sc1
	global_load_dword v9, v16, s[42:43] offset:3584 sc1
	global_load_dword v10, v16, s[42:43] offset:3840 sc1
	global_load_dword v11, v16, s[2:3] sc1
	global_load_dword v12, v16, s[4:5] sc1
	global_load_dword v13, v16, s[6:7] sc1
	global_load_dword v14, v16, s[8:9] sc1
	s_mov_b64 s[10:11], -1
	s_mov_b64 s[12:13], -1
	s_waitcnt vmcnt(14)
	v_add_u32_e32 v17, v0, v15
	s_waitcnt vmcnt(13)
	v_add_u32_e32 v17, v17, v1
	s_waitcnt vmcnt(12)
	v_add_u32_e32 v17, v17, v2
	s_waitcnt vmcnt(11)
	v_add_u32_e32 v17, v17, v3
	s_waitcnt vmcnt(10)
	v_add_u32_e32 v17, v17, v4
	s_waitcnt vmcnt(9)
	v_add_u32_e32 v17, v17, v5
	s_waitcnt vmcnt(8)
	v_add_u32_e32 v17, v17, v6
	s_waitcnt vmcnt(7)
	v_add_u32_e32 v17, v17, v7
	s_waitcnt vmcnt(6)
	v_add_u32_e32 v17, v17, v8
	s_waitcnt vmcnt(5)
	v_add_u32_e32 v17, v17, v9
	s_waitcnt vmcnt(4)
	v_add_u32_e32 v17, v17, v10
	s_waitcnt vmcnt(3)
	v_add_u32_e32 v17, v17, v11
	s_waitcnt vmcnt(2)
	v_add_u32_e32 v17, v17, v12
	s_waitcnt vmcnt(1)
	v_add_u32_e32 v17, v17, v13
	s_waitcnt vmcnt(0)
	v_add_u32_e32 v17, v17, v14
	v_cmp_eq_u32_e32 vcc, s16, v17
	s_cbranch_vccnz .LBB0_2188
	s_and_b32 s10, s17, 0xff
	s_cmp_eq_u32 s10, 0
	s_mov_b64 s[10:11], -1
	s_mov_b64 s[14:15], -1
	s_nop 0
	s_cbranch_scc0 .LBB0_2193
	global_load_dword v17, v16, s[42:43] offset:512 sc1
	s_waitcnt vmcnt(0)
	v_cmp_eq_u32_e32 vcc, 0, v17
	s_cbranch_vccnz .LBB0_2195
	s_mov_b64 s[14:15], 0

; __device__ __forceinline__ unsigned xb_ld(unsigned* p)              { return __hip_atomic_load(p, __ATOMIC_RELAXED, __HIP_MEMORY_SCOPE_AGENT); }
; __device__ __forceinline__ unsigned xb_add(unsigned* p, unsigned v) { return __hip_atomic_fetch_add(p, v, __ATOMIC_RELAXED, __HIP_MEMORY_SCOPE_AGENT); }
; #define XB_SPIN(cond, bar) do { unsigned _sp = 0; while (cond) { __builtin_amdgcn_s_sleep(1); \
;     if ((++_sp & 255u) == 0u) { if (xb_ld(&(bar)[XB_TMO])) break; if (_sp > XB_SPIN_CAP) { atomicAdd(&(bar)[XB_TMO], 1u); break; } } } } while (0)
; template <bool FLUSH> __device__ __forceinline__ void xcd_barrier(const XcdBarrier& b) {
;     ...
;             const unsigned og = xb_add(&bar[XB_TOP], 1u);
;             const unsigned tg = og / nx;
;             if (og + 1u == (tg + 1u) * nx) xb_add(&bar[XB_TOPGEN], 1u);
;             else XB_SPIN(xb_ld(&bar[XB_TOPGEN]) == tg, bar);
;             __builtin_amdgcn_fence(__ATOMIC_ACQUIRE, "agent");
;             xb_add(&bar[XB_XGEN(b.x)], 1u);
;             asm volatile("s_waitcnt vmcnt(0)" ::: "memory");
;         } else {
;             XB_SPIN(xb_ld(&bar[XB_XGEN(b.x)]) == gen, bar);
;             __builtin_amdgcn_fence(__ATOMIC_ACQUIRE, "agent");
;             asm volatile("s_waitcnt vmcnt(0)" ::: "memory");
;         }
.LBB0_2203:
	s_and_b32 s16, s20, 0xff
	s_mov_b64 s[14:15], -1
	s_cmp_lg_u32 s16, 0
	s_mov_b64 s[18:19], -1
	s_nop 0
	s_cbranch_scc1 .LBB0_2206
	global_load_dword v2, v0, s[42:43] offset:512 sc1
	s_waitcnt vmcnt(0)
	v_cmp_eq_u32_e32 vcc, 0, v2
	s_cbranch_vccnz .LBB0_2208
	s_mov_b64 s[18:19], 0
	s_mov_b64 s[16:17], -1

; __device__ __forceinline__ unsigned xb_ld(unsigned* p)              { return __hip_atomic_load(p, __ATOMIC_RELAXED, __HIP_MEMORY_SCOPE_AGENT); }
; __device__ __forceinline__ unsigned xb_add(unsigned* p, unsigned v) { return __hip_atomic_fetch_add(p, v, __ATOMIC_RELAXED, __HIP_MEMORY_SCOPE_AGENT); }
; #define XB_SPIN(cond, bar) do { unsigned _sp = 0; while (cond) { __builtin_amdgcn_s_sleep(1); \
;     if ((++_sp & 255u) == 0u) { if (xb_ld(&(bar)[XB_TMO])) break; if (_sp > XB_SPIN_CAP) { atomicAdd(&(bar)[XB_TMO], 1u); break; } } } } while (0)
; template <bool FLUSH> __device__ __forceinline__ void xcd_barrier(const XcdBarrier& b) {
;     ...
;             const unsigned og = xb_add(&bar[XB_TOP], 1u);
;             const unsigned tg = og / nx;
;             if (og + 1u == (tg + 1u) * nx) xb_add(&bar[XB_TOPGEN], 1u);
;             else XB_SPIN(xb_ld(&bar[XB_TOPGEN]) == tg, bar);
;             __builtin_amdgcn_fence(__ATOMIC_ACQUIRE, "agent");
;             xb_add(&bar[XB_XGEN(b.x)], 1u);
;             asm volatile("s_waitcnt vmcnt(0)" ::: "memory");
;         } else {
;             XB_SPIN(xb_ld(&bar[XB_XGEN(b.x)]) == gen, bar);
;             __builtin_amdgcn_fence(__ATOMIC_ACQUIRE, "agent");
;             asm volatile("s_waitcnt vmcnt(0)" ::: "memory");
;         }
.LBB0_2217:
	s_and_b32 s16, s22, 0xff
	s_cmp_lg_u32 s16, 0
	s_mov_b64 s[18:19], -1
	s_nop 0
	s_cbranch_scc1 .LBB0_2220
	global_load_dword v1, v0, s[8:9] sc1
	s_waitcnt vmcnt(0)
	v_cmp_eq_u32_e32 vcc, 0, v1
	s_cbranch_vccnz .LBB0_2222
	s_mov_b64 s[18:19], 0
	s_mov_b64 s[16:17], -1
